# GDN scan loop: second read segment (9 more LDS fragment reads) also renamed and batched with counted lgkmcnt waits
# baseline (speedup 1.0000x reference)
.LBB0_1099:
	s_or_b64 exec, exec, s[10:11]
	ds_read_b128 v[64:67], v170 offset:24576
	s_waitcnt lgkmcnt(0)
	v_mfma_f32_32x32x16_bf16 v[64:79], v[64:67], v[112:115], 0
	ds_read_b128 v[176:179], v170 offset:25600
	ds_read_b128 v[180:183], v170 offset:26624
	ds_read_b128 v[184:187], v170 offset:27648
	ds_read_b128 v[188:191], v170 offset:28672
	ds_read_b128 v[192:195], v170 offset:29696
	ds_read_b128 v[196:199], v170 offset:30720
	ds_read_b128 v[200:203], v170 offset:31744
	ds_read_b128 v[214:217], v170 offset:53248
	ds_read_b128 v[218:221], v170 offset:55296
	s_waitcnt lgkmcnt(8)
	v_mfma_f32_32x32x16_bf16 v[64:79], v[176:179], v[116:119], v[64:79]
	s_waitcnt lgkmcnt(7)
	v_mfma_f32_32x32x16_bf16 v[64:79], v[180:183], v[120:123], v[64:79]
	s_waitcnt lgkmcnt(6)
	v_mfma_f32_32x32x16_bf16 v[64:79], v[184:187], v[124:127], v[64:79]
	s_waitcnt lgkmcnt(5)
	v_mfma_f32_32x32x16_bf16 v[64:79], v[188:191], v[128:131], v[64:79]
	s_waitcnt lgkmcnt(4)
	v_mfma_f32_32x32x16_bf16 v[64:79], v[192:195], v[132:135], v[64:79]
	s_waitcnt lgkmcnt(3)
	v_mfma_f32_32x32x16_bf16 v[64:79], v[196:199], v[136:139], v[64:79]
	s_waitcnt lgkmcnt(2)
	v_mfma_f32_32x32x16_bf16 v[64:79], v[200:203], v[140:143], v[64:79]
	s_waitcnt lgkmcnt(1)
	v_mfma_f32_32x32x16_bf16 v[64:79], v[214:217], v[144:147], v[64:79]
	ds_read_b128 v[112:115], v170 offset:54272
	s_waitcnt lgkmcnt(0)
	v_mfma_f32_32x32x16_bf16 v[64:79], v[112:115], v[80:83], v[64:79]
	s_waitcnt lgkmcnt(0)
	v_mfma_f32_32x32x16_bf16 v[64:79], v[218:221], v[88:91], v[64:79]
	ds_read_b128 v[80:83], v170 offset:56320
	s_waitcnt lgkmcnt(0)
	v_mfma_f32_32x32x16_bf16 v[64:79], v[80:83], v[84:87], v[64:79]
	v_mov_b32_e32 v80, 0
	s_nop 10
	v_mov_b32_dpp v80, v64 quad_perm:[1,0,3,2] row_mask:0xf bank_mask:0xf
	s_and_saveexec_b64 s[10:11], vcc
	s_cbranch_execz .LBB0_1101
	v_bfe_u32 v82, v64, 16, 1
	s_movk_i32 s14, 0x7fff
	v_add3_u32 v64, v64, v82, s14
	v_bfe_u32 v82, v80, 16, 1
	v_lshrrev_b32_e32 v64, 16, v64
	v_add3_u32 v80, v80, v82, s14
	s_mov_b32 s14, 0xffff0000
	v_add_u32_e32 v81, 32, v92
	v_and_or_b32 v64, v80, s14, v64
	s_movk_i32 s14, 0x600
	v_mad_i64_i32 v[80:81], s[14:15], v81, s14, v[150:151]
	global_store_dword v[80:81], v64, off
